# SGU item: XOR-swizzled transposed V image in LDS (16-way write bank conflict removed), readers apply the same swizzle
# baseline (speedup 1.0000x reference)
; #define LAS __attribute__((address_space(3)))
; #define OPQV(x) asm volatile("" : "+v"(x))
; DEV void sgu_item(LAS unsigned char* lds, const bf16_t* P, const bf16_t* VN, const float* sgu_w, const float* sgu_b, bf16_t* OC, int item) {
;     int tid = threadIdx.x; OPQV(tid); const int lane = tid & 63, wv = tid >> 6, fr = lane & 15, g4 = lane >> 4;
;     LAS bf16_t* VT = (LAS bf16_t*)lds;
;     const int g = item & 7, ch = (item >> 3) & 15, b = item >> 7;
;     const size_t tok0 = (size_t)b * S_ + ch * 128;
;     const int t = wv * 16 + fr;
;     const size_t tok = tok0 + t;
;     u32x4 vin[4];
; #pragma unroll
;     for (int it = 0; it < 4; ++it) { const int idx = it * 512 + tid, s = idx >> 4, c8 = (idx & 15) * 8; vin[it] = *(const u32x4*)(VN + (tok0 + s) * 1024 + g * 128 + c8); }
;     const float* wrow = sgu_w + ((size_t)g * 128 + t) * 128;
;     f32x4 wa[4], wb[4];
; #pragma unroll
;     for (int ks = 0; ks < 4; ++ks) { wa[ks] = *(const f32x4*)(wrow + ks * 32 + g4 * 8); wb[ks] = *(const f32x4*)(wrow + ks * 32 + g4 * 8 + 4); }
;     u32x2 uu[8];
; #pragma unroll
;     for (int n = 0; n < 8; ++n) uu[n] = *(const u32x2*)(P + tok * NP + COL_U + g * 128 + n * 16 + g4 * 4);
;     const float bias = sgu_b[g * 128 + t];
; #pragma unroll
;     for (int it = 0; it < 4; ++it) { const int idx = it * 512 + tid, s = idx >> 4, c8 = (idx & 15) * 8;
; #pragma unroll
;         for (int j = 0; j < 4; ++j) { VT[(c8 + 2 * j) * 136 + s] = (bf16_t)(vin[it][j] & 0xffffu); VT[(c8 + 2 * j + 1) * 136 + s] = (bf16_t)(vin[it][j] >> 16); } }
;     __syncthreads();
.LBB0_164:
	s_or_b64 exec, exec, s[4:5]
	v_mov_b32_e32 v0, s95
	s_waitcnt lgkmcnt(0)
	s_barrier
	ds_read_b32 v0, v0
	s_movk_i32 s4, 0x7ff
	s_waitcnt lgkmcnt(0)
	s_barrier
	v_cmp_lt_i32_e32 vcc, s4, v0
	v_readfirstlane_b32 s43, v0
	s_mov_b64 s[4:5], -1
	s_cbranch_vccnz .LBB0_159
	s_cmpk_gt_i32 s43, 0x3ff
	s_cbranch_scc0 .LBB0_167
	s_add_i32 s4, s43, 0xfffffc00
	s_lshl_b32 s5, s4, 4
	s_lshl_b32 s4, s4, 7
	v_mov_b32_e32 v8, v210
	s_and_b32 s6, s4, 0x380
	s_and_b32 s36, s5, 0x3f80
	v_lshlrev_b32_e32 v0, 3, v8
	s_lshl_b32 s4, s6, 1
	v_and_b32_e32 v9, 0x78, v0
	s_add_u32 s44, s34, s4
	v_ashrrev_i32_e32 v4, 4, v8
	s_addc_u32 s45, s35, 0
	v_lshlrev_b32_e32 v0, 1, v9
	v_ashrrev_i32_e32 v5, 31, v4
	v_lshl_add_u64 v[2:3], s[44:45], 0, v[0:1]
	v_lshl_add_u64 v[6:7], v[4:5], 0, s[36:37]
	v_add_u32_e32 v0, 0x200, v8
	v_lshlrev_b64 v[6:7], 11, v[6:7]
	v_ashrrev_i32_e32 v70, 4, v0
	v_lshl_add_u64 v[6:7], v[2:3], 0, v[6:7]
	v_ashrrev_i32_e32 v71, 31, v70
	global_load_dwordx4 v[30:33], v[6:7], off
	v_lshl_add_u64 v[6:7], v[70:71], 0, s[36:37]
	v_add_u32_e32 v0, 0x400, v8
	v_lshlrev_b64 v[6:7], 11, v[6:7]
	v_ashrrev_i32_e32 v72, 4, v0
	v_lshl_add_u64 v[6:7], v[2:3], 0, v[6:7]
	v_ashrrev_i32_e32 v73, 31, v72
	global_load_dwordx4 v[34:37], v[6:7], off
	v_lshl_add_u64 v[6:7], v[72:73], 0, s[36:37]
	v_add_u32_e32 v0, 0x600, v8
	v_lshlrev_b64 v[6:7], 11, v[6:7]
	v_ashrrev_i32_e32 v74, 4, v0
	v_lshl_add_u64 v[6:7], v[2:3], 0, v[6:7]
	v_ashrrev_i32_e32 v75, 31, v74
	global_load_dwordx4 v[38:41], v[6:7], off
	v_lshl_add_u64 v[6:7], v[74:75], 0, s[36:37]
	v_ashrrev_i32_e32 v0, 2, v8
	v_lshlrev_b64 v[6:7], 11, v[6:7]
	s_waitcnt vmcnt(11)
	v_bfi_b32 v28, -16, v0, v8
	v_lshl_add_u64 v[2:3], v[2:3], 0, v[6:7]
	v_ashrrev_i32_e32 v29, 31, v28
	s_mov_b32 s7, s37
	global_load_dwordx4 v[42:45], v[2:3], off
	v_lshl_add_u64 v[2:3], v[28:29], 0, s[6:7]
	v_bfe_u32 v0, v8, 4, 2
	v_lshlrev_b64 v[2:3], 9, v[2:3]
	v_lshl_add_u64 v[2:3], s[80:81], 0, v[2:3]
	v_lshlrev_b32_e32 v6, 5, v0
	v_mov_b32_e32 v7, v1
	v_lshl_add_u64 v[6:7], v[2:3], 0, v[6:7]
	global_load_dwordx4 v[46:49], v[6:7], off
	global_load_dwordx4 v[50:53], v[6:7], off offset:16
	v_mov_b64_e32 v[2:3], s[76:77]
	v_and_b32_e32 v82, 15, v8
	v_add_u32_e32 v8, s6, v28
	s_movk_i32 s6, 0x110
	v_lshl_add_u64 v[24:25], v[28:29], 0, s[36:37]
	s_mov_b32 s5, s37
	v_mad_u32_u24 v71, v9, s6, 0
	v_ashrrev_i32_e32 v9, 31, v8
	v_mad_i64_i32 v[2:3], s[6:7], v24, s59, v[2:3]
	v_and_b32_e32 v208, 7, v210
	v_lshlrev_b32_e32 v208, 3, v208
	v_xor_b32_e32 v209, v208, v4
	v_lshl_add_u32 v73, v209, 1, v71
	v_lshlrev_b32_e32 v0, 3, v0
	v_lshl_add_u64 v[4:5], v[8:9], 2, s[82:83]
	v_lshl_add_u64 v[2:3], v[2:3], 0, s[4:5]
	global_load_dword v29, v[4:5], off
	v_lshl_add_u64 v[10:11], v[2:3], 0, v[0:1]
	global_load_dwordx4 v[54:57], v[6:7], off offset:144
	global_load_dwordx4 v[58:61], v[6:7], off offset:128
	global_load_dwordx4 v[62:65], v[6:7], off offset:272
	global_load_dwordx4 v[66:69], v[6:7], off offset:256
	global_load_dwordx4 v[2:5], v[6:7], off offset:400
	s_nop 0
	global_load_dwordx4 v[6:9], v[6:7], off offset:384
	s_mov_b64 s[6:7], 0x2c00
	s_movk_i32 s5, 0x2000
	v_lshl_add_u64 v[76:77], v[10:11], 0, s[6:7]
	v_add_co_u32_e32 v10, vcc, s5, v10
	v_or_b32_e32 v90, 32, v0
	s_nop 0
	v_addc_co_u32_e32 v11, vcc, 0, v11, vcc
	global_load_dwordx2 v[22:23], v[76:77], off offset:32
	global_load_dwordx2 v[20:21], v[76:77], off offset:64
	global_load_dwordx2 v[18:19], v[76:77], off offset:96
	global_load_dwordx2 v[16:17], v[76:77], off offset:128
	global_load_dwordx2 v[26:27], v[10:11], off offset:3072
	global_load_dwordx2 v[14:15], v[76:77], off offset:160
	global_load_dwordx2 v[12:13], v[76:77], off offset:192
	s_nop 0
	global_load_dwordx2 v[10:11], v[76:77], off offset:224
	v_cmp_le_i32_e32 vcc, v0, v28
	v_or_b32_e32 v91, 33, v0
	s_movk_i32 s5, 0x88
	v_mad_u32_u24 v83, v82, s5, v227
	v_mad_u32_u24 v84, v82, s5, v252
	v_mad_u32_u24 v85, v82, s5, v216
	v_mad_u32_u24 v86, v82, s5, v217
	v_mad_u32_u24 v87, v82, s5, v218
	s_waitcnt vmcnt(20)
	ds_write_b16 v73, v30
	ds_write_b16_d16_hi v73, v30 offset:272
	ds_write_b16 v73, v31 offset:544
	ds_write_b16_d16_hi v73, v31 offset:816
	ds_write_b16 v73, v32 offset:1088
	ds_write_b16_d16_hi v73, v32 offset:1360
	ds_write_b16 v73, v33 offset:1632
	ds_write_b16_d16_hi v73, v33 offset:1904
	v_xor_b32_e32 v209, v208, v70
	v_lshl_add_u32 v30, v209, 1, v71
	s_waitcnt vmcnt(19)
	ds_write_b16 v30, v34
	ds_write_b16_d16_hi v30, v34 offset:272
	ds_write_b16 v30, v35 offset:544
	ds_write_b16_d16_hi v30, v35 offset:816
	ds_write_b16 v30, v36 offset:1088
	ds_write_b16_d16_hi v30, v36 offset:1360
	ds_write_b16 v30, v37 offset:1632
	ds_write_b16_d16_hi v30, v37 offset:1904
	v_xor_b32_e32 v209, v208, v72
	v_lshl_add_u32 v30, v209, 1, v71
	s_waitcnt vmcnt(18)
	ds_write_b16 v30, v38
	ds_write_b16_d16_hi v30, v38 offset:272
	ds_write_b16 v30, v39 offset:544
	ds_write_b16_d16_hi v30, v39 offset:816
	ds_write_b16 v30, v40 offset:1088
	ds_write_b16_d16_hi v30, v40 offset:1360
	ds_write_b16 v30, v41 offset:1632
	ds_write_b16_d16_hi v30, v41 offset:1904
	v_xor_b32_e32 v209, v208, v74
	v_lshl_add_u32 v30, v209, 1, v71
	s_waitcnt vmcnt(17)
	ds_write_b16 v30, v42
	ds_write_b16_d16_hi v30, v42 offset:272
	ds_write_b16 v30, v43 offset:544
	ds_write_b16_d16_hi v30, v43 offset:816
	ds_write_b16 v30, v44 offset:1088
	ds_write_b16_d16_hi v30, v44 offset:1360
	ds_write_b16 v30, v45 offset:1632
	ds_write_b16_d16_hi v30, v45 offset:1904
	v_or_b32_e32 v32, 2, v0
	v_or_b32_e32 v33, 3, v0
	v_or_b32_e32 v34, 4, v0
	v_or_b32_e32 v35, 5, v0
	v_or_b32_e32 v36, 6, v0
	v_or_b32_e32 v37, 7, v0
	s_waitcnt vmcnt(16) lgkmcnt(0)
	v_cndmask_b32_e32 v30, 0, v46, vcc
	v_cmp_lt_i32_e32 vcc, v0, v28
	s_barrier
; #define LAS __attribute__((address_space(3)))
; DEV u32x4 pack8(const float (&f)[8]) { u32x4 w; w.x = cvt_pk_bf16(f[0], f[1]); w.y = cvt_pk_bf16(f[2], f[3]); w.z = cvt_pk_bf16(f[4], f[5]); w.w = cvt_pk_bf16(f[6], f[7]); return w; }
; DEV void sgu_item(LAS unsigned char* lds, const bf16_t* P, const bf16_t* VN, const float* sgu_w, const float* sgu_b, bf16_t* OC, int item) {
;     ...
; #pragma unroll
;     for (int ks = 0; ks < 4; ++ks) { const int s0 = ks * 32 + g4 * 8;
;         float wf[8] = {wa[ks][0], wa[ks][1], wa[ks][2], wa[ks][3], wb[ks][0], wb[ks][1], wb[ks][2], wb[ks][3]};
; #pragma unroll
;         for (int j = 0; j < 8; ++j) if (s0 + j > t) wf[j] = 0.f;
;         const bf16x8 wfr = as_bf16x8(pack8(wf));
; #pragma unroll
;         for (int n = 0; n < 8; ++n) { const bf16x8 vf = *(const LAS bf16x8*)(lds + ((n * 16 + fr) * 136 + s0) * 2);
;             acc[n] = __builtin_amdgcn_mfma_f32_16x16x32_bf16(vf, wfr, acc[n], 0, 0, 0); } }
	v_and_b32_e32 v199, 8, v82
	v_xor_b32_e32 v200, v199, v0
	v_or_b32_e32 v201, 32, v200
	v_or_b32_e32 v202, 64, v200
	v_or_b32_e32 v203, 0x60, v200
	v_xor_b32_e32 v204, 16, v200
	v_or_b32_e32 v205, 32, v204
	v_or_b32_e32 v206, 64, v204
	v_or_b32_e32 v207, 0x60, v204
	s_nop 0
	v_cndmask_b32_e32 v31, 0, v47, vcc
	v_cmp_le_i32_e32 vcc, v32, v28
	v_cvt_pk_bf16_f32 v30, v30, v31
	v_mad_u32_u24 v88, v82, s5, v219
	v_mad_u32_u24 v89, v82, s5, v220
	v_cndmask_b32_e32 v32, 0, v48, vcc
	v_cmp_le_i32_e32 vcc, v33, v28
	v_add_u32_e32 v38, v204, v83
	v_add_u32_e32 v42, v201, v84
	v_cndmask_b32_e32 v33, 0, v49, vcc
	v_cmp_le_i32_e32 vcc, v34, v28
	v_cvt_pk_bf16_f32 v31, v32, v33
	v_add_u32_e32 v46, v205, v85
	v_add_u32_e32 v70, v204, v87
	s_waitcnt vmcnt(15)
	v_cndmask_b32_e32 v34, 0, v50, vcc
	v_cmp_le_i32_e32 vcc, v35, v28
	v_add_u32_e32 v50, v200, v86
	v_add_u32_e32 v74, v201, v88
	v_cndmask_b32_e32 v35, 0, v51, vcc
	v_cmp_le_i32_e32 vcc, v36, v28
	v_cvt_pk_bf16_f32 v32, v34, v35
	v_mad_u32_u24 v34, v82, s5, v200
	v_lshl_add_u32 v34, v34, 1, 0
	v_cndmask_b32_e32 v36, 0, v52, vcc
	v_cmp_le_i32_e32 vcc, v37, v28
	v_add_u32_e32 v78, v205, v89
	v_lshl_add_u32 v38, v38, 1, 0
	v_cndmask_b32_e32 v37, 0, v53, vcc
	v_cmp_le_i32_e32 vcc, v90, v28
	v_cvt_pk_bf16_f32 v33, v36, v37
	ds_read_b128 v[34:37], v34
	ds_read_b128 v[38:41], v38
	s_waitcnt vmcnt(12)
	v_cndmask_b32_e32 v58, 0, v58, vcc
	v_cmp_le_i32_e32 vcc, v91, v28
	v_or_b32_e32 v91, 34, v0
	v_lshl_add_u32 v42, v42, 1, 0
	v_cndmask_b32_e32 v59, 0, v59, vcc
	v_cmp_le_i32_e32 vcc, v91, v28
	v_or_b32_e32 v91, 35, v0
	v_lshl_add_u32 v46, v46, 1, 0
	v_cndmask_b32_e32 v60, 0, v60, vcc
	v_cmp_le_i32_e32 vcc, v91, v28
	v_or_b32_e32 v91, 36, v0
	v_lshl_add_u32 v50, v50, 1, 0
	v_cndmask_b32_e32 v61, 0, v61, vcc
	v_cmp_le_i32_e32 vcc, v91, v28
	v_lshl_add_u32 v70, v70, 1, 0
	v_lshl_add_u32 v74, v74, 1, 0
	v_cndmask_b32_e32 v91, 0, v54, vcc
	v_or_b32_e32 v54, 37, v0
	v_cmp_le_i32_e32 vcc, v54, v28
	v_or_b32_e32 v54, 38, v0
	v_lshl_add_u32 v78, v78, 1, 0
	v_cndmask_b32_e32 v92, 0, v55, vcc
	v_cmp_le_i32_e32 vcc, v54, v28
	v_or_b32_e32 v54, 39, v0
	ds_read_b128 v[42:45], v42
	ds_read_b128 v[46:49], v46
	ds_read_b128 v[50:53], v50
	ds_read_b128 v[70:73], v70
	ds_read_b128 v[74:77], v74
	ds_read_b128 v[78:81], v78
	v_cndmask_b32_e32 v93, 0, v56, vcc
	v_cmp_le_i32_e32 vcc, v54, v28
	v_cvt_pk_bf16_f32 v54, v58, v59
	v_mad_u32_u24 v58, v82, s5, v201
	v_lshl_add_u32 v58, v58, 1, 0
	v_cndmask_b32_e32 v57, 0, v57, vcc
	v_cvt_pk_bf16_f32 v55, v60, v61
	v_cvt_pk_bf16_f32 v56, v91, v92
	v_cvt_pk_bf16_f32 v57, v93, v57
	ds_read_b128 v[58:61], v58
	s_waitcnt lgkmcnt(8)
	v_mfma_f32_16x16x32_bf16 v[34:37], v[34:37], v[30:33], 0
	v_lshlrev_b64 v[24:25], 11, v[24:25]
	v_lshl_add_u64 v[24:25], s[88:89], 0, v[24:25]
	s_waitcnt lgkmcnt(7)
	v_mfma_f32_16x16x32_bf16 v[38:41], v[38:41], v[30:33], 0
	s_waitcnt lgkmcnt(6)
	v_mfma_f32_16x16x32_bf16 v[42:45], v[42:45], v[30:33], 0
	s_waitcnt lgkmcnt(5)
	v_mfma_f32_16x16x32_bf16 v[46:49], v[46:49], v[30:33], 0
	s_waitcnt lgkmcnt(4)
	v_mfma_f32_16x16x32_bf16 v[50:53], v[50:53], v[30:33], 0
	s_waitcnt lgkmcnt(3)
	v_mfma_f32_16x16x32_bf16 v[70:73], v[70:73], v[30:33], 0
	s_waitcnt lgkmcnt(2)
	v_mfma_f32_16x16x32_bf16 v[74:77], v[74:77], v[30:33], 0
	s_waitcnt lgkmcnt(1)
	v_mfma_f32_16x16x32_bf16 v[30:33], v[78:81], v[30:33], 0
	v_add_u32_e32 v78, v205, v83
	v_lshl_add_u32 v78, v78, 1, 0
	ds_read_b128 v[78:81], v78
	s_waitcnt lgkmcnt(1)
	v_mfma_f32_16x16x32_bf16 v[34:37], v[58:61], v[54:57], v[34:37]
	v_add_u32_e32 v58, v200, v84
	v_lshl_add_u32 v58, v58, 1, 0
	ds_read_b128 v[58:61], v58
	s_waitcnt lgkmcnt(1)
	v_mfma_f32_16x16x32_bf16 v[38:41], v[78:81], v[54:57], v[38:41]
	v_add_u32_e32 v78, v204, v85
	v_lshl_add_u32 v78, v78, 1, 0
	ds_read_b128 v[78:81], v78
	s_waitcnt lgkmcnt(1)
	v_mfma_f32_16x16x32_bf16 v[42:45], v[58:61], v[54:57], v[42:45]
	v_add_u32_e32 v58, v201, v86
	v_lshl_add_u32 v58, v58, 1, 0
	ds_read_b128 v[58:61], v58
	s_waitcnt lgkmcnt(1)
	v_mfma_f32_16x16x32_bf16 v[46:49], v[78:81], v[54:57], v[46:49]
	v_add_u32_e32 v78, v205, v87
	v_lshl_add_u32 v78, v78, 1, 0
	ds_read_b128 v[78:81], v78
	s_waitcnt lgkmcnt(1)
	v_mfma_f32_16x16x32_bf16 v[50:53], v[58:61], v[54:57], v[50:53]
	v_add_u32_e32 v58, v200, v88
	v_lshl_add_u32 v58, v58, 1, 0
	ds_read_b128 v[58:61], v58
	s_waitcnt lgkmcnt(1)
	v_mfma_f32_16x16x32_bf16 v[70:73], v[78:81], v[54:57], v[70:73]
	v_add_u32_e32 v78, v204, v89
	v_lshl_add_u32 v78, v78, 1, 0
	ds_read_b128 v[78:81], v78
	s_waitcnt lgkmcnt(1)
	v_mfma_f32_16x16x32_bf16 v[58:61], v[58:61], v[54:57], v[74:77]
	s_nop 2
	v_or_b32_e32 v74, 64, v0
	v_cmp_le_i32_e32 vcc, v74, v28
	v_or_b32_e32 v75, 0x41, v0
	s_waitcnt lgkmcnt(0)
	v_mfma_f32_16x16x32_bf16 v[30:33], v[78:81], v[54:57], v[30:33]
	s_waitcnt vmcnt(10)
	v_cndmask_b32_e32 v66, 0, v66, vcc
	v_cmp_le_i32_e32 vcc, v75, v28
	v_or_b32_e32 v75, 0x42, v0
	v_add_u32_e32 v54, v206, v83
	v_cndmask_b32_e32 v67, 0, v67, vcc
	v_cmp_le_i32_e32 vcc, v75, v28
	v_or_b32_e32 v75, 0x43, v0
	v_lshl_add_u32 v54, v54, 1, 0
	v_cndmask_b32_e32 v68, 0, v68, vcc
	v_cmp_le_i32_e32 vcc, v75, v28
	v_or_b32_e32 v75, 0x44, v0
	s_nop 0
	v_cndmask_b32_e32 v69, 0, v69, vcc
	v_cmp_le_i32_e32 vcc, v75, v28
	s_nop 1
	v_cndmask_b32_e32 v75, 0, v62, vcc
	v_or_b32_e32 v62, 0x45, v0
	v_cmp_le_i32_e32 vcc, v62, v28
	v_or_b32_e32 v62, 0x46, v0
	s_nop 0
	v_cndmask_b32_e32 v76, 0, v63, vcc
	v_cmp_le_i32_e32 vcc, v62, v28
	v_or_b32_e32 v62, 0x47, v0
	s_nop 0
	v_cndmask_b32_e32 v77, 0, v64, vcc
	v_cmp_le_i32_e32 vcc, v62, v28
	v_cvt_pk_bf16_f32 v62, v66, v67
	v_mad_u32_u24 v66, v82, s5, v202
	v_lshl_add_u32 v66, v66, 1, 0
	v_cndmask_b32_e32 v65, 0, v65, vcc
	v_cvt_pk_bf16_f32 v63, v68, v69
	v_cvt_pk_bf16_f32 v64, v75, v76
	v_cvt_pk_bf16_f32 v65, v77, v65
	ds_read_b128 v[66:69], v66
	ds_read_b128 v[54:57], v54
	s_waitcnt lgkmcnt(1)
; #define LAS __attribute__((address_space(3)))
; DEV float bflo(unsigned u) { return __uint_as_float(u << 16); }
; DEV float bfhi(unsigned u) { return __uint_as_float(u & 0xffff0000u); }
; DEV unsigned cvt_pk_bf16(float lo, float hi) { unsigned r; asm volatile("v_cvt_pk_bf16_f32 %0, %1, %2" : "=v"(r) : "v"(lo), "v"(hi)); return r; }
; DEV u32x4 pack8(const float (&f)[8]) { u32x4 w; w.x = cvt_pk_bf16(f[0], f[1]); w.y = cvt_pk_bf16(f[2], f[3]); w.z = cvt_pk_bf16(f[4], f[5]); w.w = cvt_pk_bf16(f[6], f[7]); return w; }
; DEV void sgu_item(LAS unsigned char* lds, const bf16_t* P, const bf16_t* VN, const float* sgu_w, const float* sgu_b, bf16_t* OC, int item) {
;     ...
; #pragma unroll
;     for (int ks = 0; ks < 4; ++ks) { const int s0 = ks * 32 + g4 * 8;
;         float wf[8] = {wa[ks][0], wa[ks][1], wa[ks][2], wa[ks][3], wb[ks][0], wb[ks][1], wb[ks][2], wb[ks][3]};
; #pragma unroll
;         for (int j = 0; j < 8; ++j) if (s0 + j > t) wf[j] = 0.f;
;         const bf16x8 wfr = as_bf16x8(pack8(wf));
; #pragma unroll
;         for (int n = 0; n < 8; ++n) { const bf16x8 vf = *(const LAS bf16x8*)(lds + ((n * 16 + fr) * 136 + s0) * 2);
;             acc[n] = __builtin_amdgcn_mfma_f32_16x16x32_bf16(vf, wfr, acc[n], 0, 0, 0); } }
; #pragma unroll
;     for (int n = 0; n < 8; ++n) { const int c = g * 128 + n * 16 + g4 * 4;
;         u32x2 w; w.x = cvt_pk_bf16(bflo(uu[n].x) * (acc[n][0] + bias), bfhi(uu[n].x) * (acc[n][1] + bias)); w.y = cvt_pk_bf16(bflo(uu[n].y) * (acc[n][2] + bias), bfhi(uu[n].y) * (acc[n][3] + bias));
;         *(u32x2*)(OC + tok * 1024 + c) = w; }
	v_mfma_f32_16x16x32_bf16 v[34:37], v[66:69], v[62:65], v[34:37]
	v_add_u32_e32 v66, v203, v84
	v_lshl_add_u32 v66, v66, 1, 0
	ds_read_b128 v[66:69], v66
	s_waitcnt lgkmcnt(1)
	v_mfma_f32_16x16x32_bf16 v[38:41], v[54:57], v[62:65], v[38:41]
	v_add_u32_e32 v54, v207, v85
	v_lshl_add_u32 v54, v54, 1, 0
	ds_read_b128 v[54:57], v54
	s_waitcnt lgkmcnt(1)
	v_mfma_f32_16x16x32_bf16 v[42:45], v[66:69], v[62:65], v[42:45]
	v_add_u32_e32 v66, v202, v86
	v_lshl_add_u32 v66, v66, 1, 0
	ds_read_b128 v[66:69], v66
	s_waitcnt lgkmcnt(1)
	v_mfma_f32_16x16x32_bf16 v[46:49], v[54:57], v[62:65], v[46:49]
	v_add_u32_e32 v54, v206, v87
	v_lshl_add_u32 v54, v54, 1, 0
	ds_read_b128 v[54:57], v54
	s_waitcnt lgkmcnt(1)
	v_mfma_f32_16x16x32_bf16 v[50:53], v[66:69], v[62:65], v[50:53]
	v_add_u32_e32 v66, v203, v88
	v_lshl_add_u32 v66, v66, 1, 0
	ds_read_b128 v[66:69], v66
	s_waitcnt lgkmcnt(1)
	v_mfma_f32_16x16x32_bf16 v[54:57], v[54:57], v[62:65], v[70:73]
	s_nop 2
	v_add_u32_e32 v70, v207, v89
	v_lshl_add_u32 v70, v70, 1, 0
	ds_read_b128 v[70:73], v70
	s_waitcnt lgkmcnt(1)
	v_mfma_f32_16x16x32_bf16 v[58:61], v[66:69], v[62:65], v[58:61]
	v_or_b32_e32 v66, 0x60, v0
	v_cmp_le_i32_e32 vcc, v66, v28
	v_or_b32_e32 v67, 0x61, v0
	s_waitcnt lgkmcnt(0)
	v_mfma_f32_16x16x32_bf16 v[30:33], v[70:73], v[62:65], v[30:33]
	s_waitcnt vmcnt(8)
	v_cndmask_b32_e32 v6, 0, v6, vcc
	v_cmp_le_i32_e32 vcc, v67, v28
	v_or_b32_e32 v67, 0x62, v0
	s_nop 0
	v_cndmask_b32_e32 v7, 0, v7, vcc
	v_cmp_le_i32_e32 vcc, v67, v28
	v_or_b32_e32 v67, 0x63, v0
	s_nop 0
	v_cndmask_b32_e32 v8, 0, v8, vcc
	v_cmp_le_i32_e32 vcc, v67, v28
	v_or_b32_e32 v67, 0x64, v0
	s_nop 0
	v_cndmask_b32_e32 v9, 0, v9, vcc
	v_cmp_le_i32_e32 vcc, v67, v28
	s_nop 1
	v_cndmask_b32_e32 v67, 0, v2, vcc
	v_or_b32_e32 v2, 0x65, v0
	v_cmp_le_i32_e32 vcc, v2, v28
	v_or_b32_e32 v2, 0x66, v0
	s_nop 0
	v_cndmask_b32_e32 v68, 0, v3, vcc
	v_cmp_le_i32_e32 vcc, v2, v28
	v_or_b32_e32 v2, 0x67, v0
	v_or_b32_e32 v0, s4, v0
	v_cndmask_b32_e32 v69, 0, v4, vcc
	v_cmp_le_i32_e32 vcc, v2, v28
	v_cvt_pk_bf16_f32 v2, v6, v7
	v_mad_u32_u24 v6, v82, s5, v203
	v_lshl_add_u32 v6, v6, 1, 0
	v_cndmask_b32_e32 v5, 0, v5, vcc
	v_cvt_pk_bf16_f32 v3, v8, v9
	v_cvt_pk_bf16_f32 v4, v67, v68
	v_cvt_pk_bf16_f32 v5, v69, v5
	ds_read_b128 v[6:9], v6
	v_add_u32_e32 v28, v207, v83
	v_lshl_add_u32 v28, v28, 1, 0
	ds_read_b128 v[62:65], v28
	v_add_u32_e32 v28, v202, v84
	v_lshl_add_u32 v28, v28, 1, 0
	s_waitcnt lgkmcnt(1)
	v_mfma_f32_16x16x32_bf16 v[6:9], v[6:9], v[2:5], v[34:37]
	s_nop 2
	ds_read_b128 v[34:37], v28
	v_add_u32_e32 v28, v206, v85
	v_lshl_add_u32 v28, v28, 1, 0
	s_waitcnt lgkmcnt(1)
	v_mfma_f32_16x16x32_bf16 v[38:41], v[62:65], v[2:5], v[38:41]
	ds_read_b128 v[62:65], v28
	v_add_u32_e32 v28, v203, v86
	v_lshl_add_u32 v28, v28, 1, 0
	s_waitcnt lgkmcnt(1)
	v_mfma_f32_16x16x32_bf16 v[34:37], v[34:37], v[2:5], v[42:45]
	v_add_f32_e32 v6, v29, v6
	s_nop 1
	ds_read_b128 v[42:45], v28
	v_add_u32_e32 v28, v207, v87
	v_lshl_add_u32 v28, v28, 1, 0
	s_waitcnt lgkmcnt(1)
	v_mfma_f32_16x16x32_bf16 v[46:49], v[62:65], v[2:5], v[46:49]
	ds_read_b128 v[62:65], v28
	v_add_u32_e32 v28, v202, v88
	v_lshl_add_u32 v28, v28, 1, 0
	s_waitcnt lgkmcnt(1)
	v_mfma_f32_16x16x32_bf16 v[42:45], v[42:45], v[2:5], v[50:53]
	v_add_f32_e32 v7, v29, v7
	s_nop 1
	ds_read_b128 v[50:53], v28
	v_add_u32_e32 v28, v206, v89
	v_lshl_add_u32 v28, v28, 1, 0
	s_waitcnt lgkmcnt(1)
	v_mfma_f32_16x16x32_bf16 v[54:57], v[62:65], v[2:5], v[54:57]
	ds_read_b128 v[62:65], v28
	s_waitcnt vmcnt(3)
; DEV float bflo(unsigned u) { return __uint_as_float(u << 16); }
; DEV float bfhi(unsigned u) { return __uint_as_float(u & 0xffff0000u); }
; DEV unsigned cvt_pk_bf16(float lo, float hi) { unsigned r; asm volatile("v_cvt_pk_bf16_f32 %0, %1, %2" : "=v"(r) : "v"(lo), "v"(hi)); return r; }
; DEV void sgu_item(LAS unsigned char* lds, const bf16_t* P, const bf16_t* VN, const float* sgu_w, const float* sgu_b, bf16_t* OC, int item) {
;     ...
; #pragma unroll
;     for (int n = 0; n < 8; ++n) { const int c = g * 128 + n * 16 + g4 * 4;
;         u32x2 w; w.x = cvt_pk_bf16(bflo(uu[n].x) * (acc[n][0] + bias), bfhi(uu[n].x) * (acc[n][1] + bias)); w.y = cvt_pk_bf16(bflo(uu[n].y) * (acc[n][2] + bias), bfhi(uu[n].y) * (acc[n][3] + bias));
;         *(u32x2*)(OC + tok * 1024 + c) = w; }
;     __syncthreads();
	v_lshlrev_b32_e32 v28, 16, v26
	v_and_b32_e32 v26, 0xffff0000, v26
	v_mul_f32_e32 v6, v6, v28
	v_mul_f32_e32 v7, v7, v26
	v_cvt_pk_bf16_f32 v6, v6, v7
	v_lshlrev_b32_e32 v7, 16, v27
	v_add_f32_e32 v8, v29, v8
	v_mul_f32_e32 v7, v8, v7
	v_and_b32_e32 v8, 0xffff0000, v27
	v_add_f32_e32 v9, v29, v9
	v_mul_f32_e32 v8, v9, v8
	v_cvt_pk_bf16_f32 v7, v7, v8
	v_lshl_add_u64 v[8:9], v[24:25], 0, v[0:1]
	global_store_dwordx2 v[8:9], v[6:7], off
	v_lshlrev_b32_e32 v0, 16, v22
	v_add_f32_e32 v6, v29, v38
	v_mul_f32_e32 v0, v6, v0
	v_and_b32_e32 v6, 0xffff0000, v22
	v_add_f32_e32 v7, v29, v39
	v_mul_f32_e32 v6, v7, v6
	v_cvt_pk_bf16_f32 v6, v0, v6
	v_lshlrev_b32_e32 v0, 16, v23
	v_add_f32_e32 v7, v29, v40
	v_mul_f32_e32 v0, v7, v0
	v_and_b32_e32 v7, 0xffff0000, v23
	v_add_f32_e32 v22, v29, v41
	v_mul_f32_e32 v7, v22, v7
	v_cvt_pk_bf16_f32 v7, v0, v7
	global_store_dwordx2 v[8:9], v[6:7], off offset:32
	v_lshlrev_b32_e32 v0, 16, v20
	v_add_f32_e32 v6, v29, v34
	v_mul_f32_e32 v0, v6, v0
	v_and_b32_e32 v6, 0xffff0000, v20
	v_add_f32_e32 v7, v29, v35
	v_mul_f32_e32 v6, v7, v6
	v_cvt_pk_bf16_f32 v6, v0, v6
	v_lshlrev_b32_e32 v0, 16, v21
	v_add_f32_e32 v7, v29, v36
	v_mul_f32_e32 v0, v7, v0
	v_and_b32_e32 v7, 0xffff0000, v21
	v_add_f32_e32 v20, v29, v37
	v_mul_f32_e32 v7, v20, v7
	v_cvt_pk_bf16_f32 v7, v0, v7
	global_store_dwordx2 v[8:9], v[6:7], off offset:64
	v_lshlrev_b32_e32 v0, 16, v18
	v_add_f32_e32 v6, v29, v46
	v_mul_f32_e32 v0, v6, v0
	v_and_b32_e32 v6, 0xffff0000, v18
	v_add_f32_e32 v7, v29, v47
	v_mul_f32_e32 v6, v7, v6
	v_cvt_pk_bf16_f32 v6, v0, v6
	v_lshlrev_b32_e32 v0, 16, v19
	v_add_f32_e32 v7, v29, v48
	v_mul_f32_e32 v0, v7, v0
	v_and_b32_e32 v7, 0xffff0000, v19
	v_add_f32_e32 v18, v29, v49
	v_mul_f32_e32 v7, v18, v7
	v_cvt_pk_bf16_f32 v7, v0, v7
	global_store_dwordx2 v[8:9], v[6:7], off offset:96
	v_lshlrev_b32_e32 v0, 16, v16
	v_add_f32_e32 v6, v29, v42
	v_mul_f32_e32 v0, v6, v0
	v_and_b32_e32 v6, 0xffff0000, v16
	v_add_f32_e32 v7, v29, v43
	v_mul_f32_e32 v6, v7, v6
	v_cvt_pk_bf16_f32 v6, v0, v6
	v_lshlrev_b32_e32 v0, 16, v17
	v_add_f32_e32 v7, v29, v44
	v_mul_f32_e32 v0, v7, v0
	v_and_b32_e32 v7, 0xffff0000, v17
	v_add_f32_e32 v16, v29, v45
	v_mul_f32_e32 v7, v16, v7
	v_cvt_pk_bf16_f32 v7, v0, v7
	global_store_dwordx2 v[8:9], v[6:7], off offset:128
	s_waitcnt vmcnt(7)
	v_lshlrev_b32_e32 v0, 16, v14
	v_add_f32_e32 v6, v29, v54
	v_mul_f32_e32 v0, v6, v0
	v_and_b32_e32 v6, 0xffff0000, v14
	v_add_f32_e32 v7, v29, v55
	s_waitcnt lgkmcnt(1)
	v_mfma_f32_16x16x32_bf16 v[50:53], v[50:53], v[2:5], v[58:61]
	v_mul_f32_e32 v6, v7, v6
	v_cvt_pk_bf16_f32 v6, v0, v6
	v_lshlrev_b32_e32 v0, 16, v15
	v_add_f32_e32 v7, v29, v56
	v_mul_f32_e32 v0, v7, v0
	v_and_b32_e32 v7, 0xffff0000, v15
	v_add_f32_e32 v14, v29, v57
	v_mul_f32_e32 v7, v14, v7
	v_cvt_pk_bf16_f32 v7, v0, v7
	global_store_dwordx2 v[8:9], v[6:7], off offset:160
	s_waitcnt vmcnt(7)
	v_lshlrev_b32_e32 v0, 16, v12
	v_add_f32_e32 v6, v29, v50
	v_mul_f32_e32 v0, v6, v0
	v_and_b32_e32 v6, 0xffff0000, v12
	v_add_f32_e32 v7, v29, v51
	s_waitcnt lgkmcnt(0)
	v_mfma_f32_16x16x32_bf16 v[2:5], v[62:65], v[2:5], v[30:33]
	v_mul_f32_e32 v6, v7, v6
	v_cvt_pk_bf16_f32 v6, v0, v6
	v_lshlrev_b32_e32 v0, 16, v13
	v_add_f32_e32 v7, v29, v52
	v_mul_f32_e32 v0, v7, v0
	v_and_b32_e32 v7, 0xffff0000, v13
	v_add_f32_e32 v12, v29, v53
	v_mul_f32_e32 v7, v12, v7
	v_cvt_pk_bf16_f32 v7, v0, v7
	s_waitcnt vmcnt(6)
	v_lshlrev_b32_e32 v0, 16, v10
	v_add_f32_e32 v2, v29, v2
	v_mul_f32_e32 v0, v2, v0
	v_and_b32_e32 v2, 0xffff0000, v10
	v_add_f32_e32 v3, v29, v3
	v_mul_f32_e32 v2, v3, v2
	global_store_dwordx2 v[8:9], v[6:7], off offset:192
	v_cvt_pk_bf16_f32 v2, v0, v2
	v_lshlrev_b32_e32 v0, 16, v11
	v_add_f32_e32 v3, v29, v4
	v_mul_f32_e32 v0, v3, v0
	v_and_b32_e32 v3, 0xffff0000, v11
	v_add_f32_e32 v4, v29, v5
	v_mul_f32_e32 v3, v4, v3
	v_cvt_pk_bf16_f32 v3, v0, v3
	global_store_dwordx2 v[8:9], v[2:3], off offset:224
	s_barrier
	s_mov_b64 s[4:5], 0
